# P + hand-generated EpiSwiglu epilogue (scalar math; ~70 fewer VALU instructions per wave than hipcc's, all row-stat loads first)
# speedup vs baseline: 1.0015x; 1.0015x over previous
; __device__ __forceinline__ unsigned cvt_pk_bf16(float lo, float hi) { unsigned r; asm volatile("v_cvt_pk_bf16_f32 %0, %1, %2" : "=v"(r) : "v"(lo), "v"(hi)); return r; }
; __device__ __forceinline__ float row_ms(const float* ssq, int row, int fq) {
;     const f32x4 a = *(const f32x4*)(ssq + (size_t)row * 32 + fq * 8), b = *(const f32x4*)(ssq + (size_t)row * 32 + fq * 8 + 4);
;     float s = ((a[0] + a[1]) + (a[2] + a[3])) + ((b[0] + b[1]) + (b[2] + b[3]));
;     s += __shfl_xor(s, 16); s += __shfl_xor(s, 32);
;     return s * (1.0f / 2048.0f) + 1e-6f;
; }
;     __device__ __forceinline__ void operator()(const f32x4 (&acc)[2][2][4][2], const Unit& u, int wr, int wc, int fr, int fq) const {
;         const int row0 = u.pm * BM + wr * 64 + fr, col0 = u.pn * HALF + wc * 32 + 8 * fq;
; #pragma unroll
;         for (int ai = 0; ai < 2; ++ai)
; #pragma unroll
;             for (int m = 0; m < 4; ++m) { const int row = row0 + ai * HALF + m * 16; const float ms = row_ms(ssq, row, fq);
;                 const float cexp = -1.4426950408889634f * __builtin_amdgcn_rsqf(ms);
;                 float v[8];
; #pragma unroll
;                 for (int n = 0; n < 2; ++n)
; #pragma unroll
;                     for (int i = 0; i < 4; ++i) { const float a = acc[ai][0][m][n][i], b = acc[ai][1][m][n][i];
;                         v[n * 4 + i] = (a * b) * __builtin_amdgcn_rcpf(__builtin_fmaf(__builtin_amdgcn_exp2f(a * cexp), ms, ms)); }
;                 u32x4 w; w.x = cvt_pk_bf16(v[0], v[1]); w.y = cvt_pk_bf16(v[2], v[3]); w.z = cvt_pk_bf16(v[4], v[5]); w.w = cvt_pk_bf16(v[6], v[7]);
;                 *(u32x4*)(O + (size_t)row * ldc + col0) = w; }
.LBB0_334:
	s_waitcnt vmcnt(14)
	v_add_f32_e32 v192, v192, v193
	v_add_f32_e32 v194, v194, v195
	v_add_f32_e32 v196, v196, v197
	v_add_f32_e32 v198, v198, v199
	v_add_f32_e32 v192, v192, v194
	v_add_f32_e32 v196, v196, v198
	v_add_f32_e32 v239, v192, v196
	ds_bpermute_b32 v192, v155, v239
	s_waitcnt vmcnt(12)
	v_add_f32_e32 v200, v200, v201
	v_add_f32_e32 v202, v202, v203
	v_add_f32_e32 v204, v204, v205
	v_add_f32_e32 v206, v206, v207
	v_add_f32_e32 v200, v200, v202
	v_add_f32_e32 v204, v204, v206
	v_add_f32_e32 v240, v200, v204
	ds_bpermute_b32 v193, v155, v240
	s_waitcnt vmcnt(10)
	v_add_f32_e32 v208, v208, v209
	v_add_f32_e32 v210, v210, v211
	v_add_f32_e32 v212, v212, v213
	v_add_f32_e32 v214, v214, v215
	v_add_f32_e32 v208, v208, v210
	v_add_f32_e32 v212, v212, v214
	v_add_f32_e32 v241, v208, v212
	ds_bpermute_b32 v194, v155, v241
	s_waitcnt vmcnt(8)
	v_add_f32_e32 v216, v216, v217
	v_add_f32_e32 v218, v218, v219
	v_add_f32_e32 v220, v220, v221
	v_add_f32_e32 v222, v222, v223
	v_add_f32_e32 v216, v216, v218
	v_add_f32_e32 v220, v220, v222
	v_add_f32_e32 v242, v216, v220
	ds_bpermute_b32 v195, v155, v242
	s_waitcnt vmcnt(6)
	v_add_f32_e32 v224, v224, v225
	v_add_f32_e32 v226, v226, v227
	v_add_f32_e32 v228, v228, v229
	v_add_f32_e32 v230, v230, v231
	v_add_f32_e32 v224, v224, v226
	v_add_f32_e32 v228, v228, v230
	v_add_f32_e32 v243, v224, v228
	ds_bpermute_b32 v196, v155, v243
	s_waitcnt vmcnt(4)
	v_add_f32_e32 v232, v232, v233
	v_add_f32_e32 v234, v234, v235
	v_add_f32_e32 v156, v156, v157
	v_add_f32_e32 v158, v158, v159
	v_add_f32_e32 v232, v232, v234
	v_add_f32_e32 v156, v156, v158
	v_add_f32_e32 v244, v232, v156
	ds_bpermute_b32 v197, v155, v244
	s_waitcnt vmcnt(2)
	v_add_f32_e32 v160, v160, v161
	v_add_f32_e32 v162, v162, v163
	v_add_f32_e32 v164, v164, v165
	v_add_f32_e32 v166, v166, v167
	v_add_f32_e32 v160, v160, v162
	v_add_f32_e32 v164, v164, v166
	v_add_f32_e32 v245, v160, v164
	ds_bpermute_b32 v198, v155, v245
	s_waitcnt vmcnt(0)
	v_add_f32_e32 v168, v168, v169
	v_add_f32_e32 v170, v170, v171
	v_add_f32_e32 v172, v172, v173
	v_add_f32_e32 v174, v174, v175
	v_add_f32_e32 v168, v168, v170
	v_add_f32_e32 v172, v172, v174
	v_add_f32_e32 v246, v168, v172
	ds_bpermute_b32 v199, v155, v246
	s_waitcnt lgkmcnt(7)
	v_add_f32_e32 v239, v239, v192
	ds_bpermute_b32 v192, v247, v239
	s_waitcnt lgkmcnt(7)
	v_add_f32_e32 v240, v240, v193
	ds_bpermute_b32 v193, v247, v240
	s_waitcnt lgkmcnt(7)
	v_add_f32_e32 v241, v241, v194
	ds_bpermute_b32 v194, v247, v241
	s_waitcnt lgkmcnt(7)
	v_add_f32_e32 v242, v242, v195
	ds_bpermute_b32 v195, v247, v242
	s_waitcnt lgkmcnt(7)
	v_add_f32_e32 v243, v243, v196
	ds_bpermute_b32 v196, v247, v243
	s_waitcnt lgkmcnt(7)
	v_add_f32_e32 v244, v244, v197
	ds_bpermute_b32 v197, v247, v244
	s_waitcnt lgkmcnt(7)
	v_add_f32_e32 v245, v245, v198
	ds_bpermute_b32 v198, v247, v245
	s_waitcnt lgkmcnt(7)
	v_add_f32_e32 v246, v246, v199
	ds_bpermute_b32 v199, v247, v246
	s_waitcnt lgkmcnt(7)
	v_add_f32_e32 v239, v239, v192
	s_waitcnt lgkmcnt(6)
	v_add_f32_e32 v240, v240, v193
	s_waitcnt lgkmcnt(5)
	v_add_f32_e32 v241, v241, v194
	s_waitcnt lgkmcnt(4)
	v_add_f32_e32 v242, v242, v195
	s_waitcnt lgkmcnt(3)
	v_add_f32_e32 v243, v243, v196
	s_waitcnt lgkmcnt(2)
	v_add_f32_e32 v244, v244, v197
	s_waitcnt lgkmcnt(1)
	v_add_f32_e32 v245, v245, v198
	s_waitcnt lgkmcnt(0)
	v_add_f32_e32 v246, v246, v199
	v_fmamk_f32 v239, v239, 0x3a000000, v177
	v_fmamk_f32 v240, v240, 0x3a000000, v177
	v_fmamk_f32 v241, v241, 0x3a000000, v177
	v_fmamk_f32 v242, v242, 0x3a000000, v177
	v_fmamk_f32 v243, v243, 0x3a000000, v177
	v_fmamk_f32 v244, v244, 0x3a000000, v177
	v_fmamk_f32 v245, v245, 0x3a000000, v177
	v_fmamk_f32 v246, v246, 0x3a000000, v177
	v_rsq_f32_e32 v192, v239
	v_rsq_f32_e32 v193, v240
	v_rsq_f32_e32 v194, v241
	v_rsq_f32_e32 v195, v242
	v_rsq_f32_e32 v196, v243
	v_rsq_f32_e32 v197, v244
	v_rsq_f32_e32 v198, v245
	v_rsq_f32_e32 v199, v246
	s_nop 0
	v_mul_f32_e32 v192, 0xbfb8aa3b, v192
	v_mul_f32_e32 v193, 0xbfb8aa3b, v193
	v_mul_f32_e32 v194, 0xbfb8aa3b, v194
	v_mul_f32_e32 v195, 0xbfb8aa3b, v195
	v_mul_f32_e32 v196, 0xbfb8aa3b, v196
	v_mul_f32_e32 v197, 0xbfb8aa3b, v197
	v_mul_f32_e32 v198, 0xbfb8aa3b, v198
	v_mul_f32_e32 v199, 0xbfb8aa3b, v199
	v_mul_f32_e32 v124, v116, v124
	v_mul_f32_e32 v125, v117, v125
	v_mul_f32_e32 v126, v118, v126
	v_mul_f32_e32 v127, v119, v127
	v_mul_f32_e32 v120, v112, v120
	v_mul_f32_e32 v121, v113, v121
	v_mul_f32_e32 v122, v114, v122
	v_mul_f32_e32 v123, v115, v123
	v_mul_f32_e32 v116, v116, v192
	v_mul_f32_e32 v117, v117, v192
	v_mul_f32_e32 v118, v118, v192
	v_mul_f32_e32 v119, v119, v192
	v_mul_f32_e32 v112, v112, v192
	v_mul_f32_e32 v113, v113, v192
	v_mul_f32_e32 v114, v114, v192
	v_mul_f32_e32 v115, v115, v192
	v_exp_f32_e32 v116, v116
	v_exp_f32_e32 v117, v117
	v_exp_f32_e32 v118, v118
	v_exp_f32_e32 v119, v119
	v_exp_f32_e32 v112, v112
	v_exp_f32_e32 v113, v113
	v_exp_f32_e32 v114, v114
	v_exp_f32_e32 v115, v115
	v_fma_f32 v116, v116, v239, v239
	v_fma_f32 v117, v117, v239, v239
	v_fma_f32 v118, v118, v239, v239
	v_fma_f32 v119, v119, v239, v239
	v_fma_f32 v112, v112, v239, v239
	v_fma_f32 v113, v113, v239, v239
	v_fma_f32 v114, v114, v239, v239
	v_fma_f32 v115, v115, v239, v239
	v_rcp_f32_e32 v116, v116
	v_rcp_f32_e32 v117, v117
	v_rcp_f32_e32 v118, v118
	v_rcp_f32_e32 v119, v119
	v_rcp_f32_e32 v112, v112
	v_rcp_f32_e32 v113, v113
	v_rcp_f32_e32 v114, v114
	v_rcp_f32_e32 v115, v115
	v_mul_f32_e32 v124, v124, v116
	v_mul_f32_e32 v125, v125, v117
	v_mul_f32_e32 v126, v126, v118
	v_mul_f32_e32 v127, v127, v119
	v_mul_f32_e32 v120, v120, v112
	v_mul_f32_e32 v121, v121, v113
	v_mul_f32_e32 v122, v122, v114
; __device__ __forceinline__ unsigned cvt_pk_bf16(float lo, float hi) { unsigned r; asm volatile("v_cvt_pk_bf16_f32 %0, %1, %2" : "=v"(r) : "v"(lo), "v"(hi)); return r; }
;     __device__ __forceinline__ void operator()(const f32x4 (&acc)[2][2][4][2], const Unit& u, int wr, int wc, int fr, int fq) const {
;     ...
;             for (int m = 0; m < 4; ++m) { const int row = row0 + ai * HALF + m * 16; const float ms = row_ms(ssq, row, fq);
;                 const float cexp = -1.4426950408889634f * __builtin_amdgcn_rsqf(ms);
;                 float v[8];
; #pragma unroll
;                 for (int n = 0; n < 2; ++n)
; #pragma unroll
;                     for (int i = 0; i < 4; ++i) { const float a = acc[ai][0][m][n][i], b = acc[ai][1][m][n][i];
;                         v[n * 4 + i] = (a * b) * __builtin_amdgcn_rcpf(__builtin_fmaf(__builtin_amdgcn_exp2f(a * cexp), ms, ms)); }
;                 u32x4 w; w.x = cvt_pk_bf16(v[0], v[1]); w.y = cvt_pk_bf16(v[2], v[3]); w.z = cvt_pk_bf16(v[4], v[5]); w.w = cvt_pk_bf16(v[6], v[7]);
;                 *(u32x4*)(O + (size_t)row * ldc + col0) = w; }
	v_mul_f32_e32 v123, v123, v115
	v_cvt_pk_bf16_f32 v116, v124, v125
	v_cvt_pk_bf16_f32 v117, v126, v127
	v_cvt_pk_bf16_f32 v118, v120, v121
	v_cvt_pk_bf16_f32 v119, v122, v123
	global_store_dwordx4 v[188:189], v[116:119], off
	v_lshl_add_u64 v[188:189], v[188:189], 0, v[248:249]
	v_mul_f32_e32 v108, v104, v108
	v_mul_f32_e32 v109, v105, v109
	v_mul_f32_e32 v110, v106, v110
	v_mul_f32_e32 v111, v107, v111
	v_mul_f32_e32 v100, v96, v100
	v_mul_f32_e32 v101, v97, v101
	v_mul_f32_e32 v102, v98, v102
	v_mul_f32_e32 v103, v99, v103
	v_mul_f32_e32 v104, v104, v193
	v_mul_f32_e32 v105, v105, v193
	v_mul_f32_e32 v106, v106, v193
	v_mul_f32_e32 v107, v107, v193
	v_mul_f32_e32 v96, v96, v193
	v_mul_f32_e32 v97, v97, v193
	v_mul_f32_e32 v98, v98, v193
	v_mul_f32_e32 v99, v99, v193
	v_exp_f32_e32 v104, v104
	v_exp_f32_e32 v105, v105
	v_exp_f32_e32 v106, v106
	v_exp_f32_e32 v107, v107
	v_exp_f32_e32 v96, v96
	v_exp_f32_e32 v97, v97
	v_exp_f32_e32 v98, v98
	v_exp_f32_e32 v99, v99
	v_fma_f32 v104, v104, v240, v240
	v_fma_f32 v105, v105, v240, v240
	v_fma_f32 v106, v106, v240, v240
	v_fma_f32 v107, v107, v240, v240
	v_fma_f32 v96, v96, v240, v240
	v_fma_f32 v97, v97, v240, v240
	v_fma_f32 v98, v98, v240, v240
	v_fma_f32 v99, v99, v240, v240
	v_rcp_f32_e32 v104, v104
	v_rcp_f32_e32 v105, v105
	v_rcp_f32_e32 v106, v106
	v_rcp_f32_e32 v107, v107
	v_rcp_f32_e32 v96, v96
	v_rcp_f32_e32 v97, v97
	v_rcp_f32_e32 v98, v98
	v_rcp_f32_e32 v99, v99
	v_mul_f32_e32 v108, v108, v104
	v_mul_f32_e32 v109, v109, v105
	v_mul_f32_e32 v110, v110, v106
	v_mul_f32_e32 v111, v111, v107
	v_mul_f32_e32 v100, v100, v96
	v_mul_f32_e32 v101, v101, v97
	v_mul_f32_e32 v102, v102, v98
	v_mul_f32_e32 v103, v103, v99
	v_cvt_pk_bf16_f32 v104, v108, v109
	v_cvt_pk_bf16_f32 v105, v110, v111
	v_cvt_pk_bf16_f32 v106, v100, v101
	v_cvt_pk_bf16_f32 v107, v102, v103
	global_store_dwordx4 v[188:189], v[104:107], off
	v_lshl_add_u64 v[188:189], v[188:189], 0, v[248:249]
	v_mul_f32_e32 v92, v88, v92
	v_mul_f32_e32 v93, v89, v93
	v_mul_f32_e32 v94, v90, v94
	v_mul_f32_e32 v95, v91, v95
	v_mul_f32_e32 v84, v80, v84
	v_mul_f32_e32 v85, v81, v85
	v_mul_f32_e32 v86, v82, v86
	v_mul_f32_e32 v87, v83, v87
	v_mul_f32_e32 v88, v88, v194
	v_mul_f32_e32 v89, v89, v194
	v_mul_f32_e32 v90, v90, v194
	v_mul_f32_e32 v91, v91, v194
	v_mul_f32_e32 v80, v80, v194
	v_mul_f32_e32 v81, v81, v194
	v_mul_f32_e32 v82, v82, v194
	v_mul_f32_e32 v83, v83, v194
	v_exp_f32_e32 v88, v88
	v_exp_f32_e32 v89, v89
	v_exp_f32_e32 v90, v90
	v_exp_f32_e32 v91, v91
	v_exp_f32_e32 v80, v80
	v_exp_f32_e32 v81, v81
	v_exp_f32_e32 v82, v82
	v_exp_f32_e32 v83, v83
	v_fma_f32 v88, v88, v241, v241
	v_fma_f32 v89, v89, v241, v241
	v_fma_f32 v90, v90, v241, v241
	v_fma_f32 v91, v91, v241, v241
	v_fma_f32 v80, v80, v241, v241
	v_fma_f32 v81, v81, v241, v241
	v_fma_f32 v82, v82, v241, v241
	v_fma_f32 v83, v83, v241, v241
	v_rcp_f32_e32 v88, v88
	v_rcp_f32_e32 v89, v89
	v_rcp_f32_e32 v90, v90
	v_rcp_f32_e32 v91, v91
	v_rcp_f32_e32 v80, v80
	v_rcp_f32_e32 v81, v81
	v_rcp_f32_e32 v82, v82
	v_rcp_f32_e32 v83, v83
	v_mul_f32_e32 v92, v92, v88
	v_mul_f32_e32 v93, v93, v89
	v_mul_f32_e32 v94, v94, v90
	v_mul_f32_e32 v95, v95, v91
	v_mul_f32_e32 v84, v84, v80
	v_mul_f32_e32 v85, v85, v81
	v_mul_f32_e32 v86, v86, v82
	v_mul_f32_e32 v87, v87, v83
	v_cvt_pk_bf16_f32 v88, v92, v93
	v_cvt_pk_bf16_f32 v89, v94, v95
	v_cvt_pk_bf16_f32 v90, v84, v85
	v_cvt_pk_bf16_f32 v91, v86, v87
	global_store_dwordx4 v[188:189], v[88:91], off
	v_lshl_add_u64 v[188:189], v[188:189], 0, v[248:249]
	v_mul_f32_e32 v76, v72, v76
	v_mul_f32_e32 v77, v73, v77
	v_mul_f32_e32 v78, v74, v78
	v_mul_f32_e32 v79, v75, v79
	v_mul_f32_e32 v68, v64, v68
	v_mul_f32_e32 v69, v65, v69
	v_mul_f32_e32 v70, v66, v70
	v_mul_f32_e32 v71, v67, v71
	v_mul_f32_e32 v72, v72, v195
	v_mul_f32_e32 v73, v73, v195
	v_mul_f32_e32 v74, v74, v195
	v_mul_f32_e32 v75, v75, v195
	v_mul_f32_e32 v64, v64, v195
	v_mul_f32_e32 v65, v65, v195
	v_mul_f32_e32 v66, v66, v195
	v_mul_f32_e32 v67, v67, v195
	v_exp_f32_e32 v72, v72
	v_exp_f32_e32 v73, v73
	v_exp_f32_e32 v74, v74
	v_exp_f32_e32 v75, v75
	v_exp_f32_e32 v64, v64
	v_exp_f32_e32 v65, v65
	v_exp_f32_e32 v66, v66
	v_exp_f32_e32 v67, v67
	v_fma_f32 v72, v72, v242, v242
	v_fma_f32 v73, v73, v242, v242
	v_fma_f32 v74, v74, v242, v242
	v_fma_f32 v75, v75, v242, v242
	v_fma_f32 v64, v64, v242, v242
	v_fma_f32 v65, v65, v242, v242
	v_fma_f32 v66, v66, v242, v242
	v_fma_f32 v67, v67, v242, v242
	v_rcp_f32_e32 v72, v72
	v_rcp_f32_e32 v73, v73
	v_rcp_f32_e32 v74, v74
	v_rcp_f32_e32 v75, v75
	v_rcp_f32_e32 v64, v64
	v_rcp_f32_e32 v65, v65
	v_rcp_f32_e32 v66, v66
	v_rcp_f32_e32 v67, v67
	v_mul_f32_e32 v76, v76, v72
	v_mul_f32_e32 v77, v77, v73
	v_mul_f32_e32 v78, v78, v74
	v_mul_f32_e32 v79, v79, v75
	v_mul_f32_e32 v68, v68, v64
	v_mul_f32_e32 v69, v69, v65
	v_mul_f32_e32 v70, v70, v66
	v_mul_f32_e32 v71, v71, v67
	v_cvt_pk_bf16_f32 v72, v76, v77
	v_cvt_pk_bf16_f32 v73, v78, v79
	v_cvt_pk_bf16_f32 v74, v68, v69
	v_cvt_pk_bf16_f32 v75, v70, v71
	global_store_dwordx4 v[188:189], v[72:75], off
	v_lshl_add_u64 v[188:189], v[188:189], 0, v[250:251]
	v_mul_f32_e32 v60, v56, v60
	v_mul_f32_e32 v61, v57, v61
	v_mul_f32_e32 v62, v58, v62
	v_mul_f32_e32 v63, v59, v63
	v_mul_f32_e32 v52, v48, v52
	v_mul_f32_e32 v53, v49, v53
	v_mul_f32_e32 v54, v50, v54
	v_mul_f32_e32 v55, v51, v55
	v_mul_f32_e32 v56, v56, v196
	v_mul_f32_e32 v57, v57, v196
	v_mul_f32_e32 v58, v58, v196
	v_mul_f32_e32 v59, v59, v196
	v_mul_f32_e32 v48, v48, v196
	v_mul_f32_e32 v49, v49, v196
	v_mul_f32_e32 v50, v50, v196
	v_mul_f32_e32 v51, v51, v196
	v_exp_f32_e32 v56, v56
	v_exp_f32_e32 v57, v57
	v_exp_f32_e32 v58, v58
; __device__ __forceinline__ unsigned cvt_pk_bf16(float lo, float hi) { unsigned r; asm volatile("v_cvt_pk_bf16_f32 %0, %1, %2" : "=v"(r) : "v"(lo), "v"(hi)); return r; }
; #define PG8_BAR __builtin_amdgcn_s_barrier()
;     __device__ __forceinline__ void operator()(const f32x4 (&acc)[2][2][4][2], const Unit& u, int wr, int wc, int fr, int fq) const {
;     ...
;             for (int m = 0; m < 4; ++m) { const int row = row0 + ai * HALF + m * 16; const float ms = row_ms(ssq, row, fq);
;                 const float cexp = -1.4426950408889634f * __builtin_amdgcn_rsqf(ms);
;                 float v[8];
; #pragma unroll
;                 for (int n = 0; n < 2; ++n)
; #pragma unroll
;                     for (int i = 0; i < 4; ++i) { const float a = acc[ai][0][m][n][i], b = acc[ai][1][m][n][i];
;                         v[n * 4 + i] = (a * b) * __builtin_amdgcn_rcpf(__builtin_fmaf(__builtin_amdgcn_exp2f(a * cexp), ms, ms)); }
;                 u32x4 w; w.x = cvt_pk_bf16(v[0], v[1]); w.y = cvt_pk_bf16(v[2], v[3]); w.z = cvt_pk_bf16(v[4], v[5]); w.w = cvt_pk_bf16(v[6], v[7]);
;                 *(u32x4*)(O + (size_t)row * ldc + col0) = w; }
; template <class Epi, class Sched, bool ALIGN_EPI = false, bool SP2 = false>
; __device__ __forceinline__ void gemm_phase(PG8_LAS unsigned char* lds, const Gemm g, const Sched& S, const Epi& E) {
;     ...
;         if constexpr (!Epi::AFTER_DRAIN) { E(acc, cur, wr, wc, fr, fq); S.done(cur); }
;         if (!has_next) break;
; #pragma unroll
;         for (int a = 0; a < 2; ++a)
; #pragma unroll
;             for (int b = 0; b < 2; ++b)
; #pragma unroll
;                 for (int m = 0; m < 4; ++m)
; #pragma unroll
;                     for (int n = 0; n < 2; ++n) acc[a][b][m][n] = (f32x4){0.f, 0.f, 0.f, 0.f};
;         cur = nxt; cA = nA; cB = nB; ++ui;
;         if constexpr (ALIGN_EPI) { if (wr == 1) PG8_BAR; }
	v_exp_f32_e32 v59, v59
	v_exp_f32_e32 v48, v48
	v_exp_f32_e32 v49, v49
	v_exp_f32_e32 v50, v50
	v_exp_f32_e32 v51, v51
	v_fma_f32 v56, v56, v243, v243
	v_fma_f32 v57, v57, v243, v243
	v_fma_f32 v58, v58, v243, v243
	v_fma_f32 v59, v59, v243, v243
	v_fma_f32 v48, v48, v243, v243
	v_fma_f32 v49, v49, v243, v243
	v_fma_f32 v50, v50, v243, v243
	v_fma_f32 v51, v51, v243, v243
	v_rcp_f32_e32 v56, v56
	v_rcp_f32_e32 v57, v57
	v_rcp_f32_e32 v58, v58
	v_rcp_f32_e32 v59, v59
	v_rcp_f32_e32 v48, v48
	v_rcp_f32_e32 v49, v49
	v_rcp_f32_e32 v50, v50
	v_rcp_f32_e32 v51, v51
	v_mul_f32_e32 v60, v60, v56
	v_mul_f32_e32 v61, v61, v57
	v_mul_f32_e32 v62, v62, v58
	v_mul_f32_e32 v63, v63, v59
	v_mul_f32_e32 v52, v52, v48
	v_mul_f32_e32 v53, v53, v49
	v_mul_f32_e32 v54, v54, v50
	v_mul_f32_e32 v55, v55, v51
	v_cvt_pk_bf16_f32 v56, v60, v61
	v_cvt_pk_bf16_f32 v57, v62, v63
	v_cvt_pk_bf16_f32 v58, v52, v53
	v_cvt_pk_bf16_f32 v59, v54, v55
	global_store_dwordx4 v[188:189], v[56:59], off
	v_lshl_add_u64 v[188:189], v[188:189], 0, v[248:249]
	v_mul_f32_e32 v44, v40, v44
	v_mul_f32_e32 v45, v41, v45
	v_mul_f32_e32 v46, v42, v46
	v_mul_f32_e32 v47, v43, v47
	v_mul_f32_e32 v36, v32, v36
	v_mul_f32_e32 v37, v33, v37
	v_mul_f32_e32 v38, v34, v38
	v_mul_f32_e32 v39, v35, v39
	v_mul_f32_e32 v40, v40, v197
	v_mul_f32_e32 v41, v41, v197
	v_mul_f32_e32 v42, v42, v197
	v_mul_f32_e32 v43, v43, v197
	v_mul_f32_e32 v32, v32, v197
	v_mul_f32_e32 v33, v33, v197
	v_mul_f32_e32 v34, v34, v197
	v_mul_f32_e32 v35, v35, v197
	v_exp_f32_e32 v40, v40
	v_exp_f32_e32 v41, v41
	v_exp_f32_e32 v42, v42
	v_exp_f32_e32 v43, v43
	v_exp_f32_e32 v32, v32
	v_exp_f32_e32 v33, v33
	v_exp_f32_e32 v34, v34
	v_exp_f32_e32 v35, v35
	v_fma_f32 v40, v40, v244, v244
	v_fma_f32 v41, v41, v244, v244
	v_fma_f32 v42, v42, v244, v244
	v_fma_f32 v43, v43, v244, v244
	v_fma_f32 v32, v32, v244, v244
	v_fma_f32 v33, v33, v244, v244
	v_fma_f32 v34, v34, v244, v244
	v_fma_f32 v35, v35, v244, v244
	v_rcp_f32_e32 v40, v40
	v_rcp_f32_e32 v41, v41
	v_rcp_f32_e32 v42, v42
	v_rcp_f32_e32 v43, v43
	v_rcp_f32_e32 v32, v32
	v_rcp_f32_e32 v33, v33
	v_rcp_f32_e32 v34, v34
	v_rcp_f32_e32 v35, v35
	v_mul_f32_e32 v44, v44, v40
	v_mul_f32_e32 v45, v45, v41
	v_mul_f32_e32 v46, v46, v42
	v_mul_f32_e32 v47, v47, v43
	v_mul_f32_e32 v36, v36, v32
	v_mul_f32_e32 v37, v37, v33
	v_mul_f32_e32 v38, v38, v34
	v_mul_f32_e32 v39, v39, v35
	v_cvt_pk_bf16_f32 v40, v44, v45
	v_cvt_pk_bf16_f32 v41, v46, v47
	v_cvt_pk_bf16_f32 v42, v36, v37
	v_cvt_pk_bf16_f32 v43, v38, v39
	global_store_dwordx4 v[188:189], v[40:43], off
	v_lshl_add_u64 v[188:189], v[188:189], 0, v[248:249]
	v_mul_f32_e32 v28, v24, v28
	v_mul_f32_e32 v29, v25, v29
	v_mul_f32_e32 v30, v26, v30
	v_mul_f32_e32 v31, v27, v31
	v_mul_f32_e32 v20, v16, v20
	v_mul_f32_e32 v21, v17, v21
	v_mul_f32_e32 v22, v18, v22
	v_mul_f32_e32 v23, v19, v23
	v_mul_f32_e32 v24, v24, v198
	v_mul_f32_e32 v25, v25, v198
	v_mul_f32_e32 v26, v26, v198
	v_mul_f32_e32 v27, v27, v198
	v_mul_f32_e32 v16, v16, v198
	v_mul_f32_e32 v17, v17, v198
	v_mul_f32_e32 v18, v18, v198
	v_mul_f32_e32 v19, v19, v198
	v_exp_f32_e32 v24, v24
	v_exp_f32_e32 v25, v25
	v_exp_f32_e32 v26, v26
	v_exp_f32_e32 v27, v27
	v_exp_f32_e32 v16, v16
	v_exp_f32_e32 v17, v17
	v_exp_f32_e32 v18, v18
	v_exp_f32_e32 v19, v19
	v_fma_f32 v24, v24, v245, v245
	v_fma_f32 v25, v25, v245, v245
	v_fma_f32 v26, v26, v245, v245
	v_fma_f32 v27, v27, v245, v245
	v_fma_f32 v16, v16, v245, v245
	v_fma_f32 v17, v17, v245, v245
	v_fma_f32 v18, v18, v245, v245
	v_fma_f32 v19, v19, v245, v245
	v_rcp_f32_e32 v24, v24
	v_rcp_f32_e32 v25, v25
	v_rcp_f32_e32 v26, v26
	v_rcp_f32_e32 v27, v27
	v_rcp_f32_e32 v16, v16
	v_rcp_f32_e32 v17, v17
	v_rcp_f32_e32 v18, v18
	v_rcp_f32_e32 v19, v19
	v_mul_f32_e32 v28, v28, v24
	v_mul_f32_e32 v29, v29, v25
	v_mul_f32_e32 v30, v30, v26
	v_mul_f32_e32 v31, v31, v27
	v_mul_f32_e32 v20, v20, v16
	v_mul_f32_e32 v21, v21, v17
	v_mul_f32_e32 v22, v22, v18
	v_mul_f32_e32 v23, v23, v19
	v_cvt_pk_bf16_f32 v24, v28, v29
	v_cvt_pk_bf16_f32 v25, v30, v31
	v_cvt_pk_bf16_f32 v26, v20, v21
	v_cvt_pk_bf16_f32 v27, v22, v23
	global_store_dwordx4 v[188:189], v[24:27], off
	v_lshl_add_u64 v[188:189], v[188:189], 0, v[248:249]
	v_mul_f32_e32 v12, v8, v12
	v_mul_f32_e32 v13, v9, v13
	v_mul_f32_e32 v14, v10, v14
	v_mul_f32_e32 v15, v11, v15
	v_mul_f32_e32 v0, v4, v0
	v_mul_f32_e32 v1, v5, v1
	v_mul_f32_e32 v2, v6, v2
	v_mul_f32_e32 v3, v7, v3
	v_mul_f32_e32 v8, v8, v199
	v_mul_f32_e32 v9, v9, v199
	v_mul_f32_e32 v10, v10, v199
	v_mul_f32_e32 v11, v11, v199
	v_mul_f32_e32 v4, v4, v199
	v_mul_f32_e32 v5, v5, v199
	v_mul_f32_e32 v6, v6, v199
	v_mul_f32_e32 v7, v7, v199
	v_exp_f32_e32 v8, v8
	v_exp_f32_e32 v9, v9
	v_exp_f32_e32 v10, v10
	v_exp_f32_e32 v11, v11
	v_exp_f32_e32 v4, v4
	v_exp_f32_e32 v5, v5
	v_exp_f32_e32 v6, v6
	v_exp_f32_e32 v7, v7
	v_fma_f32 v8, v8, v246, v246
	v_fma_f32 v9, v9, v246, v246
	v_fma_f32 v10, v10, v246, v246
	v_fma_f32 v11, v11, v246, v246
	v_fma_f32 v4, v4, v246, v246
	v_fma_f32 v5, v5, v246, v246
	v_fma_f32 v6, v6, v246, v246
	v_fma_f32 v7, v7, v246, v246
	v_rcp_f32_e32 v8, v8
	v_rcp_f32_e32 v9, v9
	v_rcp_f32_e32 v10, v10
	v_rcp_f32_e32 v11, v11
	v_rcp_f32_e32 v4, v4
	v_rcp_f32_e32 v5, v5
	v_rcp_f32_e32 v6, v6
	v_rcp_f32_e32 v7, v7
	v_mul_f32_e32 v12, v12, v8
	v_mul_f32_e32 v13, v13, v9
	v_mul_f32_e32 v14, v14, v10
	v_mul_f32_e32 v15, v15, v11
	v_mul_f32_e32 v0, v0, v4
	v_mul_f32_e32 v1, v1, v5
	v_mul_f32_e32 v2, v2, v6
	v_mul_f32_e32 v3, v3, v7
	v_cvt_pk_bf16_f32 v8, v12, v13
	v_cvt_pk_bf16_f32 v9, v14, v15
	v_cvt_pk_bf16_f32 v10, v0, v1
	v_cvt_pk_bf16_f32 v11, v2, v3
	global_store_dwordx4 v[188:189], v[8:11], off
	s_andn2_b64 vcc, exec, s[40:41]
	s_mov_b64 s[40:41], -1
	s_movk_i32 s81, 0x77e
	s_cbranch_vccnz .LBB0_327
	s_andn2_b64 vcc, exec, s[28:29]
	s_cbranch_vccnz .LBB0_326
	s_barrier
	s_branch .LBB0_326
